# P5: split token loop into U-phase (all 8 tokens) then V-phase so only one fp4 table is hot in L2 at a time; on top of coalesced u-pass
# speedup vs baseline: 1.0548x; 1.0281x over previous
; __global__ void __launch_bounds__(256, 2) mega(Params P) {
;     ...
; #pragma unroll 1
;             for (int tau = 0; tau < 8; ++tau) {
;                 const int t = tb + tau * tstride;
;                 if (t < T2) peer_token(P, t, lane5, sidx, sval, (const int*)(res + tau * 1024), (const float*)(res + tau * 1024 + 512), szero);
.LBB0_1381:
	s_or_b64 exec, exec, s[16:17]
	s_add_i32 s85, s85, 1
	s_cmp_eq_u32 s85, 8
	s_cbranch_scc1 .Lp5_v_start

; __device__ __forceinline__ void peer_token(const Params& P, int t, int lane, int* sidx, float* sval, const int* sid, const float* sgate, const unsigned* szero) {
;     ...
;     {
;         float* sw = (float*)sidx;
;         float wv[2];
; #pragma unroll
;         for (int hh = 0; hh < 2; ++hh) {
;             const int e = lane + 64 * hh, id = sid[e];
;             const float a = ((sw[e] + sw[128 + e]) + (sw[256 + e] + sw[384 + e])) * usc[id] * rstd;
;             wv[hh] = sgate[e] * vsc[id] * 0.5f * a * (1.f + erff(a * 0.70710678118654752f));
;         }
;         __builtin_amdgcn_s_waitcnt(0xc07f);
;         __builtin_amdgcn_wave_barrier();
;         sw[lane] = wv[0]; sw[lane + 64] = wv[1];
;     }
;     __builtin_amdgcn_s_waitcnt(0xc07f);
;     __builtin_amdgcn_wave_barrier();
;     const int half = lane >> 5, l5 = lane & 31;
;     const int lane_o = 2 * l5 + half;
;     f32x2 acc2[16];
; #pragma unroll
;     for (int j = 0; j < 16; ++j) acc2[j] = (f32x2){0.f, 0.f};
;     const unsigned char* Vb = P.ws + WS_V;
;     const unsigned vlo = (unsigned)l5 * 16u;
; #pragma unroll 1
;     for (int e0 = 0; e0 < 128; e0 += 16) {
;         uint4 vr[8];
; #pragma unroll
;         for (int q = 0; q < 8; ++q) vr[q] = *(const uint4*)(Vb + ((unsigned)sid[e0 + 2 * q + half] * 512u + vlo));
;         const float* sw = (const float*)sidx + e0;
;         const f32x4 w0 = *(const f32x4*)(sw), w1 = *(const f32x4*)(sw + 4), w2 = *(const f32x4*)(sw + 8), w3 = *(const f32x4*)(sw + 12);
.LBB0_1421:
	s_andn2_saveexec_b64 s[18:19], s[18:19]
	v_mul_f32_e32 v9, v8, v8
	v_fmamk_f32 v10, v9, 0xba1345e1, v134
	v_fmaak_f32 v10, v9, v10, 0xbcdac9b8
	v_fmaak_f32 v10, v9, v10, 0x3de703be
	v_fmaak_f32 v10, v9, v10, 0xbec09330
	v_fmaak_f32 v9, v9, v10, 0x3e0375d0
	v_fma_f32 v9, |v8|, v9, |v8|
	s_or_b64 exec, exec, s[18:19]
	v_mul_f32_e32 v0, v1, v0
	v_mul_f32_e32 v0, 0.5, v0
	v_bfi_b32 v1, s83, v6, v5
	v_mul_f32_e32 v0, v4, v0
	v_add_f32_e32 v1, 1.0, v1
	v_mul_f32_e32 v0, v0, v1
	s_waitcnt vmcnt(0)
	v_mul_f32_e32 v1, v3, v2
	v_mul_f32_e32 v1, 0.5, v1
	v_bfi_b32 v2, s83, v9, v8
	v_mul_f32_e32 v1, v7, v1
	v_add_f32_e32 v2, 1.0, v2
	v_mul_f32_e32 v1, v1, v2
	v_lshl_add_u32 v2, v131, 2, v139
	s_waitcnt lgkmcnt(0)
	ds_write2st64_b32 v2, v0, v1 offset0:2 offset1:3
	s_waitcnt lgkmcnt(0)
	s_branch .LBB0_1381
.Lp5_v_start:
	s_mov_b32 s85, 0
.Lp5_v_head:
	s_mul_i32 s16, s85, s22
	v_add_u32_e32 v112, s16, v130
	v_cmp_gt_i32_e32 vcc, s20, v112
	s_and_saveexec_b64 s[16:17], vcc
	s_cbranch_execz .Lp5_v_next
	v_ashrrev_i32_e32 v113, 31, v112
	v_lshlrev_b64 v[0:1], 11, v[112:113]
	v_lshl_add_u64 v[110:111], s[36:37], 0, v[0:1]
	v_lshl_add_u32 v139, s85, 10, v114
	v_mov_b32_e32 v42, 0
	v_lshlrev_b64 v[40:41], 10, v[112:113]
	s_mov_b32 s18, -16
	v_mov_b32_e32 v74, v139
	v_mov_b32_e32 v43, v42
	v_mov_b32_e32 v68, v42
	v_mov_b32_e32 v69, v42
	v_mov_b32_e32 v66, v42
	v_mov_b32_e32 v67, v42
	v_mov_b32_e32 v70, v42
	v_mov_b32_e32 v71, v42
	v_mov_b32_e32 v72, v42
	v_mov_b32_e32 v73, v42
	v_mov_b32_e32 v58, v42
	v_mov_b32_e32 v59, v42
	v_mov_b32_e32 v60, v42
	v_mov_b32_e32 v61, v42
	v_mov_b32_e32 v62, v42
	v_mov_b32_e32 v63, v42
	v_mov_b32_e32 v64, v42
	v_mov_b32_e32 v65, v42
	v_mov_b32_e32 v50, v42
	v_mov_b32_e32 v51, v42
	v_mov_b32_e32 v52, v42
	v_mov_b32_e32 v53, v42
	v_mov_b32_e32 v54, v42
	v_mov_b32_e32 v55, v42
	v_mov_b32_e32 v56, v42
	v_mov_b32_e32 v57, v42
	v_mov_b32_e32 v44, v42
	v_mov_b32_e32 v45, v42
	v_mov_b32_e32 v46, v42
	v_mov_b32_e32 v47, v42
	v_mov_b32_e32 v48, v42
	v_mov_b32_e32 v49, v42
.LBB0_1424:
	v_add_u32_e32 v6, v74, v128
	ds_read2_b32 v[0:1], v6 offset1:2
	ds_read2_b32 v[2:3], v6 offset0:4 offset1:6
	ds_read2_b32 v[4:5], v6 offset0:8 offset1:10
	ds_read2_b32 v[6:7], v6 offset0:12 offset1:14
	s_add_i32 s18, s18, 16
	s_waitcnt lgkmcnt(3)
	v_lshl_or_b32 v0, v0, 9, v122
	global_load_dwordx4 v[76:79], v0, s[14:15]
	v_lshl_or_b32 v0, v1, 9, v122
	global_load_dwordx4 v[36:39], v0, s[14:15]
	s_waitcnt lgkmcnt(2)
	v_lshl_or_b32 v0, v2, 9, v122
	global_load_dwordx4 v[32:35], v0, s[14:15]
	v_lshl_or_b32 v0, v3, 9, v122
	global_load_dwordx4 v[24:27], v0, s[14:15]
	s_waitcnt lgkmcnt(1)
	v_lshl_or_b32 v0, v4, 9, v122
	global_load_dwordx4 v[20:23], v0, s[14:15]
	v_lshl_or_b32 v0, v5, 9, v122
	global_load_dwordx4 v[12:15], v0, s[14:15]
	s_waitcnt lgkmcnt(0)
	v_lshl_or_b32 v0, v6, 9, v122
	global_load_dwordx4 v[8:11], v0, s[14:15]
	v_lshl_or_b32 v0, v7, 9, v122
	global_load_dwordx4 v[0:3], v0, s[14:15]
	ds_read_b128 v[80:83], v74 offset:512
	ds_read_b128 v[28:31], v74 offset:528
	ds_read_b128 v[16:19], v74 offset:544
	ds_read_b128 v[4:7], v74 offset:560
	v_add_u32_e32 v74, 64, v74
	s_waitcnt lgkmcnt(3)
	v_cndmask_b32_e64 v80, v81, v80, s[0:1]
	s_waitcnt lgkmcnt(2)
	v_cndmask_b32_e64 v28, v29, v28, s[0:1]
	v_cndmask_b32_e64 v30, v31, v30, s[0:1]
	s_waitcnt lgkmcnt(1)
	v_cndmask_b32_e64 v16, v17, v16, s[0:1]
	v_cndmask_b32_e64 v18, v19, v18, s[0:1]
	s_waitcnt lgkmcnt(0)
	v_cndmask_b32_e64 v4, v5, v4, s[0:1]
	v_cndmask_b32_e64 v6, v7, v6, s[0:1]
	s_cmpk_lt_u32 s18, 0x70
	s_waitcnt vmcnt(7)
	v_cvt_scalef32_pk_f32_fp4 v[84:85], v76, 1.0
	v_pk_fma_f32 v[68:69], v[80:81], v[84:85], v[68:69] op_sel_hi:[0,1,1]
	v_cvt_scalef32_pk_f32_fp4 v[84:85], v77, 1.0
	v_pk_fma_f32 v[58:59], v[80:81], v[84:85], v[58:59] op_sel_hi:[0,1,1]
	v_cvt_scalef32_pk_f32_fp4 v[84:85], v78, 1.0
	v_pk_fma_f32 v[50:51], v[80:81], v[84:85], v[50:51] op_sel_hi:[0,1,1]
	v_cvt_scalef32_pk_f32_fp4 v[84:85], v79, 1.0
	v_pk_fma_f32 v[44:45], v[80:81], v[84:85], v[44:45] op_sel_hi:[0,1,1]
	v_cvt_scalef32_pk_f32_fp4 v[84:85], v76, 1.0 op_sel:[1,0,0]
	v_pk_fma_f32 v[66:67], v[80:81], v[84:85], v[66:67] op_sel_hi:[0,1,1]
	v_cvt_scalef32_pk_f32_fp4 v[84:85], v77, 1.0 op_sel:[1,0,0]
	v_pk_fma_f32 v[60:61], v[80:81], v[84:85], v[60:61] op_sel_hi:[0,1,1]
	v_cvt_scalef32_pk_f32_fp4 v[84:85], v78, 1.0 op_sel:[1,0,0]
	v_pk_fma_f32 v[52:53], v[80:81], v[84:85], v[52:53] op_sel_hi:[0,1,1]
	v_cvt_scalef32_pk_f32_fp4 v[84:85], v79, 1.0 op_sel:[1,0,0]
	v_pk_fma_f32 v[46:47], v[80:81], v[84:85], v[46:47] op_sel_hi:[0,1,1]
	v_cvt_scalef32_pk_f32_fp4 v[84:85], v76, 1.0 op_sel:[0,1,0]
	v_pk_fma_f32 v[70:71], v[80:81], v[84:85], v[70:71] op_sel_hi:[0,1,1]
	v_cvt_scalef32_pk_f32_fp4 v[84:85], v77, 1.0 op_sel:[0,1,0]
	v_pk_fma_f32 v[62:63], v[80:81], v[84:85], v[62:63] op_sel_hi:[0,1,1]
	v_cvt_scalef32_pk_f32_fp4 v[84:85], v78, 1.0 op_sel:[0,1,0]
	v_pk_fma_f32 v[54:55], v[80:81], v[84:85], v[54:55] op_sel_hi:[0,1,1]
	v_cvt_scalef32_pk_f32_fp4 v[84:85], v79, 1.0 op_sel:[0,1,0]
	v_pk_fma_f32 v[48:49], v[80:81], v[84:85], v[48:49] op_sel_hi:[0,1,1]
	v_cvt_scalef32_pk_f32_fp4 v[84:85], v76, 1.0 op_sel:[1,1,0]
	v_cvt_scalef32_pk_f32_fp4 v[76:77], v77, 1.0 op_sel:[1,1,0]
	v_pk_fma_f32 v[64:65], v[80:81], v[76:77], v[64:65] op_sel_hi:[0,1,1]
	v_cvt_scalef32_pk_f32_fp4 v[76:77], v78, 1.0 op_sel:[1,1,0]
	v_pk_fma_f32 v[56:57], v[80:81], v[76:77], v[56:57] op_sel_hi:[0,1,1]
	v_cvt_scalef32_pk_f32_fp4 v[76:77], v79, 1.0 op_sel:[1,1,0]
	v_pk_fma_f32 v[42:43], v[80:81], v[76:77], v[42:43] op_sel_hi:[0,1,1]
	v_cndmask_b32_e64 v76, v83, v82, s[0:1]
	s_waitcnt vmcnt(6)
; #define FP4_AXPY(k) { acc2[k] += w * __builtin_amdgcn_cvt_scalef32_pk_f32_fp4(vr[q].x, 1.0f, k); acc2[4 + k] += w * __builtin_amdgcn_cvt_scalef32_pk_f32_fp4(vr[q].y, 1.0f, k); \
;                       acc2[8 + k] += w * __builtin_amdgcn_cvt_scalef32_pk_f32_fp4(vr[q].z, 1.0f, k); acc2[12 + k] += w * __builtin_amdgcn_cvt_scalef32_pk_f32_fp4(vr[q].w, 1.0f, k); }
; __device__ __forceinline__ void peer_token(const Params& P, int t, int lane, int* sidx, float* sval, const int* sid, const float* sgate, const unsigned* szero) {
;     ...
; #pragma unroll
;         for (int q = 0; q < 8; ++q) {
;             const float w = half ? wq[2 * q + 1] : wq[2 * q];
;     ...
;             FP4_AXPY(0) FP4_AXPY(1) FP4_AXPY(2) FP4_AXPY(3)
;     ...
;         }
	v_cvt_scalef32_pk_f32_fp4 v[78:79], v36, 1.0
	v_pk_fma_f32 v[68:69], v[76:77], v[78:79], v[68:69] op_sel_hi:[0,1,1]
	v_cvt_scalef32_pk_f32_fp4 v[78:79], v37, 1.0
	v_pk_fma_f32 v[58:59], v[76:77], v[78:79], v[58:59] op_sel_hi:[0,1,1]
	v_cvt_scalef32_pk_f32_fp4 v[78:79], v38, 1.0
	v_pk_fma_f32 v[50:51], v[76:77], v[78:79], v[50:51] op_sel_hi:[0,1,1]
	v_cvt_scalef32_pk_f32_fp4 v[78:79], v39, 1.0
	v_pk_fma_f32 v[44:45], v[76:77], v[78:79], v[44:45] op_sel_hi:[0,1,1]
	v_cvt_scalef32_pk_f32_fp4 v[78:79], v36, 1.0 op_sel:[1,0,0]
	v_pk_fma_f32 v[66:67], v[76:77], v[78:79], v[66:67] op_sel_hi:[0,1,1]
	v_cvt_scalef32_pk_f32_fp4 v[78:79], v37, 1.0 op_sel:[1,0,0]
	v_pk_fma_f32 v[60:61], v[76:77], v[78:79], v[60:61] op_sel_hi:[0,1,1]
	v_cvt_scalef32_pk_f32_fp4 v[78:79], v38, 1.0 op_sel:[1,0,0]
	v_pk_fma_f32 v[52:53], v[76:77], v[78:79], v[52:53] op_sel_hi:[0,1,1]
	v_cvt_scalef32_pk_f32_fp4 v[78:79], v39, 1.0 op_sel:[1,0,0]
	v_pk_fma_f32 v[46:47], v[76:77], v[78:79], v[46:47] op_sel_hi:[0,1,1]
	v_cvt_scalef32_pk_f32_fp4 v[78:79], v36, 1.0 op_sel:[0,1,0]
	v_pk_fma_f32 v[70:71], v[76:77], v[78:79], v[70:71] op_sel_hi:[0,1,1]
	v_cvt_scalef32_pk_f32_fp4 v[78:79], v37, 1.0 op_sel:[0,1,0]
	v_pk_fma_f32 v[62:63], v[76:77], v[78:79], v[62:63] op_sel_hi:[0,1,1]
	v_cvt_scalef32_pk_f32_fp4 v[78:79], v38, 1.0 op_sel:[0,1,0]
	v_pk_fma_f32 v[54:55], v[76:77], v[78:79], v[54:55] op_sel_hi:[0,1,1]
	v_cvt_scalef32_pk_f32_fp4 v[78:79], v39, 1.0 op_sel:[0,1,0]
	v_pk_fma_f32 v[48:49], v[76:77], v[78:79], v[48:49] op_sel_hi:[0,1,1]
	v_cvt_scalef32_pk_f32_fp4 v[78:79], v36, 1.0 op_sel:[1,1,0]
	v_cvt_scalef32_pk_f32_fp4 v[36:37], v37, 1.0 op_sel:[1,1,0]
	v_pk_fma_f32 v[36:37], v[76:77], v[36:37], v[64:65] op_sel_hi:[0,1,1]
	v_cvt_scalef32_pk_f32_fp4 v[64:65], v38, 1.0 op_sel:[1,1,0]
	v_pk_fma_f32 v[56:57], v[76:77], v[64:65], v[56:57] op_sel_hi:[0,1,1]
	s_waitcnt vmcnt(5)
	v_cvt_scalef32_pk_f32_fp4 v[64:65], v33, 1.0
	v_pk_fma_f32 v[58:59], v[28:29], v[64:65], v[58:59] op_sel_hi:[0,1,1]
	v_cvt_scalef32_pk_f32_fp4 v[64:65], v34, 1.0
	v_cvt_scalef32_pk_f32_fp4 v[38:39], v39, 1.0 op_sel:[1,1,0]
	v_pk_fma_f32 v[50:51], v[28:29], v[64:65], v[50:51] op_sel_hi:[0,1,1]
	v_cvt_scalef32_pk_f32_fp4 v[64:65], v35, 1.0
	v_pk_fma_f32 v[38:39], v[76:77], v[38:39], v[42:43] op_sel_hi:[0,1,1]
	v_cvt_scalef32_pk_f32_fp4 v[42:43], v32, 1.0
	v_pk_fma_f32 v[44:45], v[28:29], v[64:65], v[44:45] op_sel_hi:[0,1,1]
	v_cvt_scalef32_pk_f32_fp4 v[64:65], v32, 1.0 op_sel:[1,0,0]
	v_pk_fma_f32 v[42:43], v[28:29], v[42:43], v[68:69] op_sel_hi:[0,1,1]
	v_pk_fma_f32 v[64:65], v[28:29], v[64:65], v[66:67] op_sel_hi:[0,1,1]
	v_cvt_scalef32_pk_f32_fp4 v[66:67], v33, 1.0 op_sel:[1,0,0]
	v_cvt_scalef32_pk_f32_fp4 v[68:69], v33, 1.0 op_sel:[0,1,0]
	v_pk_fma_f32 v[60:61], v[28:29], v[66:67], v[60:61] op_sel_hi:[0,1,1]
	v_cvt_scalef32_pk_f32_fp4 v[66:67], v34, 1.0 op_sel:[1,0,0]
	v_pk_fma_f32 v[62:63], v[28:29], v[68:69], v[62:63] op_sel_hi:[0,1,1]
	v_cvt_scalef32_pk_f32_fp4 v[68:69], v34, 1.0 op_sel:[0,1,0]
	v_pk_fma_f32 v[52:53], v[28:29], v[66:67], v[52:53] op_sel_hi:[0,1,1]
	v_cvt_scalef32_pk_f32_fp4 v[66:67], v35, 1.0 op_sel:[1,0,0]
	v_pk_fma_f32 v[54:55], v[28:29], v[68:69], v[54:55] op_sel_hi:[0,1,1]
	v_cvt_scalef32_pk_f32_fp4 v[68:69], v35, 1.0 op_sel:[0,1,0]
	v_pk_fma_f32 v[46:47], v[28:29], v[66:67], v[46:47] op_sel_hi:[0,1,1]
	v_cvt_scalef32_pk_f32_fp4 v[66:67], v32, 1.0 op_sel:[0,1,0]
	v_pk_fma_f32 v[48:49], v[28:29], v[68:69], v[48:49] op_sel_hi:[0,1,1]
	v_cvt_scalef32_pk_f32_fp4 v[68:69], v32, 1.0 op_sel:[1,1,0]
	v_cvt_scalef32_pk_f32_fp4 v[32:33], v33, 1.0 op_sel:[1,1,0]
	v_pk_fma_f32 v[72:73], v[80:81], v[84:85], v[72:73] op_sel_hi:[0,1,1]
	v_pk_fma_f32 v[32:33], v[28:29], v[32:33], v[36:37] op_sel_hi:[0,1,1]
	v_cvt_scalef32_pk_f32_fp4 v[36:37], v34, 1.0 op_sel:[1,1,0]
	v_pk_fma_f32 v[72:73], v[76:77], v[78:79], v[72:73] op_sel_hi:[0,1,1]
	v_pk_fma_f32 v[36:37], v[28:29], v[36:37], v[56:57] op_sel_hi:[0,1,1]
	v_cvt_scalef32_pk_f32_fp4 v[34:35], v35, 1.0 op_sel:[1,1,0]
	s_waitcnt vmcnt(4)
	v_cvt_scalef32_pk_f32_fp4 v[56:57], v25, 1.0 op_sel:[1,0,0]
	v_pk_fma_f32 v[66:67], v[28:29], v[66:67], v[70:71] op_sel_hi:[0,1,1]
	v_pk_fma_f32 v[68:69], v[28:29], v[68:69], v[72:73] op_sel_hi:[0,1,1]
	v_pk_fma_f32 v[28:29], v[28:29], v[34:35], v[38:39] op_sel_hi:[0,1,1]
	v_cvt_scalef32_pk_f32_fp4 v[34:35], v24, 1.0
	v_cvt_scalef32_pk_f32_fp4 v[38:39], v25, 1.0
	v_pk_fma_f32 v[56:57], v[30:31], v[56:57], v[60:61] op_sel_hi:[0,1,1]
	v_cvt_scalef32_pk_f32_fp4 v[60:61], v25, 1.0 op_sel:[0,1,0]
	v_pk_fma_f32 v[34:35], v[30:31], v[34:35], v[42:43] op_sel_hi:[0,1,1]
	v_pk_fma_f32 v[38:39], v[30:31], v[38:39], v[58:59] op_sel_hi:[0,1,1]
	v_cvt_scalef32_pk_f32_fp4 v[42:43], v26, 1.0
	v_cvt_scalef32_pk_f32_fp4 v[58:59], v26, 1.0 op_sel:[1,0,0]
	v_pk_fma_f32 v[60:61], v[30:31], v[60:61], v[62:63] op_sel_hi:[0,1,1]
	v_cvt_scalef32_pk_f32_fp4 v[62:63], v26, 1.0 op_sel:[0,1,0]
	v_pk_fma_f32 v[42:43], v[30:31], v[42:43], v[50:51] op_sel_hi:[0,1,1]
	v_cvt_scalef32_pk_f32_fp4 v[50:51], v27, 1.0
	v_pk_fma_f32 v[52:53], v[30:31], v[58:59], v[52:53] op_sel_hi:[0,1,1]
	v_cvt_scalef32_pk_f32_fp4 v[58:59], v27, 1.0 op_sel:[1,0,0]
	v_pk_fma_f32 v[54:55], v[30:31], v[62:63], v[54:55] op_sel_hi:[0,1,1]
	v_cvt_scalef32_pk_f32_fp4 v[62:63], v27, 1.0 op_sel:[0,1,0]
	v_pk_fma_f32 v[44:45], v[30:31], v[50:51], v[44:45] op_sel_hi:[0,1,1]
	v_cvt_scalef32_pk_f32_fp4 v[50:51], v24, 1.0 op_sel:[1,0,0]
	v_pk_fma_f32 v[46:47], v[30:31], v[58:59], v[46:47] op_sel_hi:[0,1,1]
	v_cvt_scalef32_pk_f32_fp4 v[58:59], v24, 1.0 op_sel:[0,1,0]
	v_pk_fma_f32 v[48:49], v[30:31], v[62:63], v[48:49] op_sel_hi:[0,1,1]
	v_cvt_scalef32_pk_f32_fp4 v[62:63], v24, 1.0 op_sel:[1,1,0]
	v_cvt_scalef32_pk_f32_fp4 v[24:25], v25, 1.0 op_sel:[1,1,0]
	v_pk_fma_f32 v[24:25], v[30:31], v[24:25], v[32:33] op_sel_hi:[0,1,1]
	v_cvt_scalef32_pk_f32_fp4 v[32:33], v26, 1.0 op_sel:[1,1,0]
	v_cvt_scalef32_pk_f32_fp4 v[26:27], v27, 1.0 op_sel:[1,1,0]
	v_pk_fma_f32 v[26:27], v[30:31], v[26:27], v[28:29] op_sel_hi:[0,1,1]
	s_waitcnt vmcnt(3)
; #define FP4_AXPY(k) { acc2[k] += w * __builtin_amdgcn_cvt_scalef32_pk_f32_fp4(vr[q].x, 1.0f, k); acc2[4 + k] += w * __builtin_amdgcn_cvt_scalef32_pk_f32_fp4(vr[q].y, 1.0f, k); \
;                       acc2[8 + k] += w * __builtin_amdgcn_cvt_scalef32_pk_f32_fp4(vr[q].z, 1.0f, k); acc2[12 + k] += w * __builtin_amdgcn_cvt_scalef32_pk_f32_fp4(vr[q].w, 1.0f, k); }
; __device__ __forceinline__ void peer_token(const Params& P, int t, int lane, int* sidx, float* sval, const int* sid, const float* sgate, const unsigned* szero) {
;     ...
; #pragma unroll
;         for (int q = 0; q < 8; ++q) {
;             const float w = half ? wq[2 * q + 1] : wq[2 * q];
;     ...
;             FP4_AXPY(0) FP4_AXPY(1) FP4_AXPY(2) FP4_AXPY(3)
;     ...
;         }
	v_cvt_scalef32_pk_f32_fp4 v[28:29], v20, 1.0
	v_pk_fma_f32 v[28:29], v[16:17], v[28:29], v[34:35] op_sel_hi:[0,1,1]
	v_cvt_scalef32_pk_f32_fp4 v[34:35], v22, 1.0
	v_pk_fma_f32 v[50:51], v[30:31], v[50:51], v[64:65] op_sel_hi:[0,1,1]
	v_pk_fma_f32 v[58:59], v[30:31], v[58:59], v[66:67] op_sel_hi:[0,1,1]
	v_pk_fma_f32 v[62:63], v[30:31], v[62:63], v[68:69] op_sel_hi:[0,1,1]
	v_pk_fma_f32 v[32:33], v[30:31], v[32:33], v[36:37] op_sel_hi:[0,1,1]
	v_cvt_scalef32_pk_f32_fp4 v[30:31], v21, 1.0
	v_pk_fma_f32 v[34:35], v[16:17], v[34:35], v[42:43] op_sel_hi:[0,1,1]
	v_cvt_scalef32_pk_f32_fp4 v[42:43], v21, 1.0 op_sel:[1,0,0]
	v_pk_fma_f32 v[30:31], v[16:17], v[30:31], v[38:39] op_sel_hi:[0,1,1]
	v_cvt_scalef32_pk_f32_fp4 v[36:37], v23, 1.0
	v_cvt_scalef32_pk_f32_fp4 v[38:39], v20, 1.0 op_sel:[1,0,0]
	v_pk_fma_f32 v[42:43], v[16:17], v[42:43], v[56:57] op_sel_hi:[0,1,1]
	v_cvt_scalef32_pk_f32_fp4 v[56:57], v22, 1.0 op_sel:[0,1,0]
	v_pk_fma_f32 v[36:37], v[16:17], v[36:37], v[44:45] op_sel_hi:[0,1,1]
	v_pk_fma_f32 v[38:39], v[16:17], v[38:39], v[50:51] op_sel_hi:[0,1,1]
	v_cvt_scalef32_pk_f32_fp4 v[44:45], v22, 1.0 op_sel:[1,0,0]
	v_cvt_scalef32_pk_f32_fp4 v[50:51], v23, 1.0 op_sel:[1,0,0]
	v_pk_fma_f32 v[54:55], v[16:17], v[56:57], v[54:55] op_sel_hi:[0,1,1]
	v_cvt_scalef32_pk_f32_fp4 v[56:57], v23, 1.0 op_sel:[0,1,0]
	v_pk_fma_f32 v[44:45], v[16:17], v[44:45], v[52:53] op_sel_hi:[0,1,1]
	v_pk_fma_f32 v[46:47], v[16:17], v[50:51], v[46:47] op_sel_hi:[0,1,1]
	v_cvt_scalef32_pk_f32_fp4 v[50:51], v20, 1.0 op_sel:[0,1,0]
	v_cvt_scalef32_pk_f32_fp4 v[52:53], v21, 1.0 op_sel:[0,1,0]
	v_pk_fma_f32 v[48:49], v[16:17], v[56:57], v[48:49] op_sel_hi:[0,1,1]
	v_cvt_scalef32_pk_f32_fp4 v[56:57], v20, 1.0 op_sel:[1,1,0]
	v_cvt_scalef32_pk_f32_fp4 v[20:21], v21, 1.0 op_sel:[1,1,0]
	v_pk_fma_f32 v[20:21], v[16:17], v[20:21], v[24:25] op_sel_hi:[0,1,1]
	v_cvt_scalef32_pk_f32_fp4 v[24:25], v22, 1.0 op_sel:[1,1,0]
	v_pk_fma_f32 v[24:25], v[16:17], v[24:25], v[32:33] op_sel_hi:[0,1,1]
	s_waitcnt vmcnt(2)
	v_cvt_scalef32_pk_f32_fp4 v[32:33], v12, 1.0 op_sel:[1,0,0]
	v_pk_fma_f32 v[50:51], v[16:17], v[50:51], v[58:59] op_sel_hi:[0,1,1]
	v_pk_fma_f32 v[58:59], v[18:19], v[32:33], v[38:39] op_sel_hi:[0,1,1]
	v_cvt_scalef32_pk_f32_fp4 v[32:33], v13, 1.0 op_sel:[1,0,0]
	v_pk_fma_f32 v[42:43], v[18:19], v[32:33], v[42:43] op_sel_hi:[0,1,1]
	v_cvt_scalef32_pk_f32_fp4 v[32:33], v14, 1.0 op_sel:[1,0,0]
	v_pk_fma_f32 v[44:45], v[18:19], v[32:33], v[44:45] op_sel_hi:[0,1,1]
	v_cvt_scalef32_pk_f32_fp4 v[32:33], v15, 1.0 op_sel:[1,0,0]
	v_pk_fma_f32 v[46:47], v[18:19], v[32:33], v[46:47] op_sel_hi:[0,1,1]
	v_cvt_scalef32_pk_f32_fp4 v[32:33], v12, 1.0 op_sel:[0,1,0]
	v_pk_fma_f32 v[52:53], v[16:17], v[52:53], v[60:61] op_sel_hi:[0,1,1]
	v_pk_fma_f32 v[50:51], v[18:19], v[32:33], v[50:51] op_sel_hi:[0,1,1]
	v_cvt_scalef32_pk_f32_fp4 v[32:33], v13, 1.0 op_sel:[0,1,0]
	v_pk_fma_f32 v[52:53], v[18:19], v[32:33], v[52:53] op_sel_hi:[0,1,1]
	v_cvt_scalef32_pk_f32_fp4 v[32:33], v14, 1.0 op_sel:[0,1,0]
	v_cvt_scalef32_pk_f32_fp4 v[22:23], v23, 1.0 op_sel:[1,1,0]
	v_pk_fma_f32 v[54:55], v[18:19], v[32:33], v[54:55] op_sel_hi:[0,1,1]
	v_cvt_scalef32_pk_f32_fp4 v[32:33], v15, 1.0 op_sel:[0,1,0]
	v_pk_fma_f32 v[56:57], v[16:17], v[56:57], v[62:63] op_sel_hi:[0,1,1]
	v_pk_fma_f32 v[16:17], v[16:17], v[22:23], v[26:27] op_sel_hi:[0,1,1]
	v_cvt_scalef32_pk_f32_fp4 v[22:23], v12, 1.0
	v_cvt_scalef32_pk_f32_fp4 v[26:27], v13, 1.0
	v_pk_fma_f32 v[48:49], v[18:19], v[32:33], v[48:49] op_sel_hi:[0,1,1]
	v_cvt_scalef32_pk_f32_fp4 v[32:33], v12, 1.0 op_sel:[1,1,0]
	v_cvt_scalef32_pk_f32_fp4 v[12:13], v13, 1.0 op_sel:[1,1,0]
	v_pk_fma_f32 v[22:23], v[18:19], v[22:23], v[28:29] op_sel_hi:[0,1,1]
	v_pk_fma_f32 v[26:27], v[18:19], v[26:27], v[30:31] op_sel_hi:[0,1,1]
	v_cvt_scalef32_pk_f32_fp4 v[28:29], v14, 1.0
	v_cvt_scalef32_pk_f32_fp4 v[30:31], v15, 1.0
	v_pk_fma_f32 v[12:13], v[18:19], v[12:13], v[20:21] op_sel_hi:[0,1,1]
	v_cvt_scalef32_pk_f32_fp4 v[20:21], v14, 1.0 op_sel:[1,1,0]
	v_cvt_scalef32_pk_f32_fp4 v[14:15], v15, 1.0 op_sel:[1,1,0]
	v_pk_fma_f32 v[62:63], v[18:19], v[14:15], v[16:17] op_sel_hi:[0,1,1]
	s_waitcnt vmcnt(1)
	v_cvt_scalef32_pk_f32_fp4 v[14:15], v8, 1.0
	v_pk_fma_f32 v[38:39], v[4:5], v[14:15], v[22:23] op_sel_hi:[0,1,1]
	v_cvt_scalef32_pk_f32_fp4 v[14:15], v9, 1.0
	v_pk_fma_f32 v[28:29], v[18:19], v[28:29], v[34:35] op_sel_hi:[0,1,1]
	v_pk_fma_f32 v[30:31], v[18:19], v[30:31], v[36:37] op_sel_hi:[0,1,1]
	v_pk_fma_f32 v[36:37], v[4:5], v[14:15], v[26:27] op_sel_hi:[0,1,1]
	v_cvt_scalef32_pk_f32_fp4 v[14:15], v10, 1.0
	v_pk_fma_f32 v[34:35], v[4:5], v[14:15], v[28:29] op_sel_hi:[0,1,1]
	v_cvt_scalef32_pk_f32_fp4 v[14:15], v11, 1.0
	v_pk_fma_f32 v[56:57], v[18:19], v[32:33], v[56:57] op_sel_hi:[0,1,1]
	v_pk_fma_f32 v[32:33], v[4:5], v[14:15], v[30:31] op_sel_hi:[0,1,1]
	v_cvt_scalef32_pk_f32_fp4 v[14:15], v8, 1.0 op_sel:[1,0,0]
	v_pk_fma_f32 v[30:31], v[4:5], v[14:15], v[58:59] op_sel_hi:[0,1,1]
	v_cvt_scalef32_pk_f32_fp4 v[14:15], v9, 1.0 op_sel:[1,0,0]
	v_pk_fma_f32 v[28:29], v[4:5], v[14:15], v[42:43] op_sel_hi:[0,1,1]
	v_cvt_scalef32_pk_f32_fp4 v[14:15], v10, 1.0 op_sel:[1,0,0]
	v_pk_fma_f32 v[26:27], v[4:5], v[14:15], v[44:45] op_sel_hi:[0,1,1]
	v_cvt_scalef32_pk_f32_fp4 v[14:15], v11, 1.0 op_sel:[1,0,0]
	v_pk_fma_f32 v[60:61], v[18:19], v[20:21], v[24:25] op_sel_hi:[0,1,1]
	v_pk_fma_f32 v[24:25], v[4:5], v[14:15], v[46:47] op_sel_hi:[0,1,1]
	v_cvt_scalef32_pk_f32_fp4 v[14:15], v8, 1.0 op_sel:[0,1,0]
	v_pk_fma_f32 v[22:23], v[4:5], v[14:15], v[50:51] op_sel_hi:[0,1,1]
	v_cvt_scalef32_pk_f32_fp4 v[14:15], v9, 1.0 op_sel:[0,1,0]
	v_pk_fma_f32 v[20:21], v[4:5], v[14:15], v[52:53] op_sel_hi:[0,1,1]
	v_cvt_scalef32_pk_f32_fp4 v[14:15], v10, 1.0 op_sel:[0,1,0]
	v_pk_fma_f32 v[18:19], v[4:5], v[14:15], v[54:55] op_sel_hi:[0,1,1]
	v_cvt_scalef32_pk_f32_fp4 v[14:15], v11, 1.0 op_sel:[0,1,0]
	v_pk_fma_f32 v[16:17], v[4:5], v[14:15], v[48:49] op_sel_hi:[0,1,1]
	v_cvt_scalef32_pk_f32_fp4 v[14:15], v8, 1.0 op_sel:[1,1,0]
	v_cvt_scalef32_pk_f32_fp4 v[8:9], v9, 1.0 op_sel:[1,1,0]
	v_pk_fma_f32 v[12:13], v[4:5], v[8:9], v[12:13] op_sel_hi:[0,1,1]
	v_cvt_scalef32_pk_f32_fp4 v[8:9], v10, 1.0 op_sel:[1,1,0]
	v_cvt_scalef32_pk_f32_fp4 v[10:11], v11, 1.0 op_sel:[1,1,0]
	v_pk_fma_f32 v[14:15], v[4:5], v[14:15], v[56:57] op_sel_hi:[0,1,1]
	v_pk_fma_f32 v[8:9], v[4:5], v[8:9], v[60:61] op_sel_hi:[0,1,1]
	v_pk_fma_f32 v[4:5], v[4:5], v[10:11], v[62:63] op_sel_hi:[0,1,1]
	s_waitcnt vmcnt(0)
; #define FP4_AXPY(k) { acc2[k] += w * __builtin_amdgcn_cvt_scalef32_pk_f32_fp4(vr[q].x, 1.0f, k); acc2[4 + k] += w * __builtin_amdgcn_cvt_scalef32_pk_f32_fp4(vr[q].y, 1.0f, k); \
;                       acc2[8 + k] += w * __builtin_amdgcn_cvt_scalef32_pk_f32_fp4(vr[q].z, 1.0f, k); acc2[12 + k] += w * __builtin_amdgcn_cvt_scalef32_pk_f32_fp4(vr[q].w, 1.0f, k); }
; __device__ __forceinline__ void peer_token(const Params& P, int t, int lane, int* sidx, float* sval, const int* sid, const float* sgate, const unsigned* szero) {
;     ...
; #pragma unroll 1
;     for (int e0 = 0; e0 < 128; e0 += 16) {
;         uint4 vr[8];
; #pragma unroll
;         for (int q = 0; q < 8; ++q) vr[q] = *(const uint4*)(Vb + ((unsigned)sid[e0 + 2 * q + half] * 512u + vlo));
;         const float* sw = (const float*)sidx + e0;
;         const f32x4 w0 = *(const f32x4*)(sw), w1 = *(const f32x4*)(sw + 4), w2 = *(const f32x4*)(sw + 8), w3 = *(const f32x4*)(sw + 12);
;         const float wq[16] = {w0[0], w0[1], w0[2], w0[3], w1[0], w1[1], w1[2], w1[3], w2[0], w2[1], w2[2], w2[3], w3[0], w3[1], w3[2], w3[3]};
; #pragma unroll
;         for (int q = 0; q < 8; ++q) {
;             const float w = half ? wq[2 * q + 1] : wq[2 * q];
;     ...
;             FP4_AXPY(0) FP4_AXPY(1) FP4_AXPY(2) FP4_AXPY(3)
;     ...
;         }
	v_cvt_scalef32_pk_f32_fp4 v[10:11], v0, 1.0
	v_pk_fma_f32 v[68:69], v[6:7], v[10:11], v[38:39] op_sel_hi:[0,1,1]
	v_cvt_scalef32_pk_f32_fp4 v[10:11], v1, 1.0
	v_pk_fma_f32 v[58:59], v[6:7], v[10:11], v[36:37] op_sel_hi:[0,1,1]
	v_cvt_scalef32_pk_f32_fp4 v[10:11], v2, 1.0
	v_pk_fma_f32 v[50:51], v[6:7], v[10:11], v[34:35] op_sel_hi:[0,1,1]
	v_cvt_scalef32_pk_f32_fp4 v[10:11], v3, 1.0
	v_pk_fma_f32 v[44:45], v[6:7], v[10:11], v[32:33] op_sel_hi:[0,1,1]
	v_cvt_scalef32_pk_f32_fp4 v[10:11], v0, 1.0 op_sel:[1,0,0]
	v_pk_fma_f32 v[66:67], v[6:7], v[10:11], v[30:31] op_sel_hi:[0,1,1]
	v_cvt_scalef32_pk_f32_fp4 v[10:11], v1, 1.0 op_sel:[1,0,0]
	v_pk_fma_f32 v[60:61], v[6:7], v[10:11], v[28:29] op_sel_hi:[0,1,1]
	v_cvt_scalef32_pk_f32_fp4 v[10:11], v2, 1.0 op_sel:[1,0,0]
	v_pk_fma_f32 v[52:53], v[6:7], v[10:11], v[26:27] op_sel_hi:[0,1,1]
	v_cvt_scalef32_pk_f32_fp4 v[10:11], v3, 1.0 op_sel:[1,0,0]
	v_pk_fma_f32 v[46:47], v[6:7], v[10:11], v[24:25] op_sel_hi:[0,1,1]
	v_cvt_scalef32_pk_f32_fp4 v[10:11], v0, 1.0 op_sel:[0,1,0]
	v_pk_fma_f32 v[70:71], v[6:7], v[10:11], v[22:23] op_sel_hi:[0,1,1]
	v_cvt_scalef32_pk_f32_fp4 v[10:11], v1, 1.0 op_sel:[0,1,0]
	v_pk_fma_f32 v[62:63], v[6:7], v[10:11], v[20:21] op_sel_hi:[0,1,1]
	v_cvt_scalef32_pk_f32_fp4 v[10:11], v2, 1.0 op_sel:[0,1,0]
	v_pk_fma_f32 v[54:55], v[6:7], v[10:11], v[18:19] op_sel_hi:[0,1,1]
	v_cvt_scalef32_pk_f32_fp4 v[10:11], v3, 1.0 op_sel:[0,1,0]
	v_pk_fma_f32 v[48:49], v[6:7], v[10:11], v[16:17] op_sel_hi:[0,1,1]
	v_cvt_scalef32_pk_f32_fp4 v[10:11], v0, 1.0 op_sel:[1,1,0]
	v_cvt_scalef32_pk_f32_fp4 v[0:1], v1, 1.0 op_sel:[1,1,0]
	v_pk_fma_f32 v[64:65], v[6:7], v[0:1], v[12:13] op_sel_hi:[0,1,1]
	v_cvt_scalef32_pk_f32_fp4 v[0:1], v2, 1.0 op_sel:[1,1,0]
	v_pk_fma_f32 v[56:57], v[6:7], v[0:1], v[8:9] op_sel_hi:[0,1,1]
	v_cvt_scalef32_pk_f32_fp4 v[0:1], v3, 1.0 op_sel:[1,1,0]
	v_pk_fma_f32 v[72:73], v[6:7], v[10:11], v[14:15] op_sel_hi:[0,1,1]
	v_pk_fma_f32 v[42:43], v[6:7], v[0:1], v[4:5] op_sel_hi:[0,1,1]
	s_cbranch_scc1 .LBB0_1424
; __device__ __forceinline__ void peer_token(const Params& P, int t, int lane, int* sidx, float* sval, const int* sid, const float* sgate, const unsigned* szero) {
;     ...
;     f32x2 acc[8];
; #pragma unroll
;     for (int j = 0; j < 16; ++j) {
;         const unsigned x0 = __float_as_uint(acc2[j].x), x1 = __float_as_uint(acc2[j].y);
;         const auto r0 = __builtin_amdgcn_permlane32_swap(x0, x0, false, false);
;         const auto r1 = __builtin_amdgcn_permlane32_swap(x1, x1, false, false);
;         acc2[j].x = __uint_as_float(r0[0]) + __uint_as_float(r0[1]);
;         acc2[j].y = __uint_as_float(r1[0]) + __uint_as_float(r1[1]);
;     }
; #pragma unroll
;     for (int j = 0; j < 8; ++j) { acc[j].x = half ? acc2[8 + j].x : acc2[j].x; acc[j].y = half ? acc2[8 + j].y : acc2[j].y; }
;     f32x2 xf[8];
;     {
;         const uint4 xa = *(const uint4*)(xn + lane_o * 16), xb = *(const uint4*)(xn + lane_o * 16 + 8);
;         xf[0] = (f32x2){bflo(xa.x), bfhi(xa.x)}; xf[1] = (f32x2){bflo(xa.y), bfhi(xa.y)}; xf[2] = (f32x2){bflo(xa.z), bfhi(xa.z)}; xf[3] = (f32x2){bflo(xa.w), bfhi(xa.w)};
;         xf[4] = (f32x2){bflo(xb.x), bfhi(xb.x)}; xf[5] = (f32x2){bflo(xb.y), bfhi(xb.y)}; xf[6] = (f32x2){bflo(xb.z), bfhi(xb.z)}; xf[7] = (f32x2){bflo(xb.w), bfhi(xb.w)};
;     }
;     float* o = P.out + (size_t)t * DM + lane_o * 16;
;     float4 h0, h1, h2, h3;
;     {
;         const float4 g0 = *(const float4*)(P.norm_ffn + lane_o * 16), g1 = *(const float4*)(P.norm_ffn + lane_o * 16 + 4), g2 = *(const float4*)(P.norm_ffn + lane_o * 16 + 8), g3 = *(const float4*)(P.norm_ffn + lane_o * 16 + 12);
;         h0.x = xf[0].x * __builtin_amdgcn_rcpf(g0.x) + acc[0].x; h0.y = xf[0].y * __builtin_amdgcn_rcpf(g0.y) + acc[0].y; h0.z = xf[1].x * __builtin_amdgcn_rcpf(g0.z) + acc[1].x; h0.w = xf[1].y * __builtin_amdgcn_rcpf(g0.w) + acc[1].y;
;         h1.x = xf[2].x * __builtin_amdgcn_rcpf(g1.x) + acc[2].x; h1.y = xf[2].y * __builtin_amdgcn_rcpf(g1.y) + acc[2].y; h1.z = xf[3].x * __builtin_amdgcn_rcpf(g1.z) + acc[3].x; h1.w = xf[3].y * __builtin_amdgcn_rcpf(g1.w) + acc[3].y;
;         h2.x = xf[4].x * __builtin_amdgcn_rcpf(g2.x) + acc[4].x; h2.y = xf[4].y * __builtin_amdgcn_rcpf(g2.y) + acc[4].y; h2.z = xf[5].x * __builtin_amdgcn_rcpf(g2.z) + acc[5].x; h2.w = xf[5].y * __builtin_amdgcn_rcpf(g2.w) + acc[5].y;
	v_lshl_add_u64 v[0:1], v[104:105], 1, v[110:111]
	global_load_dwordx4 v[2:5], v[108:109], off
	global_load_dwordx4 v[6:9], v[108:109], off offset:16
	global_load_dwordx4 v[10:13], v[0:1], off
	global_load_dwordx4 v[14:17], v[0:1], off offset:16
	global_load_dwordx4 v[18:21], v[108:109], off offset:32
	global_load_dwordx4 v[22:25], v[108:109], off offset:48
	v_mov_b32_e32 v26, v68
	v_mov_b32_e32 v27, v69
	v_mov_b32_e32 v29, v67
	v_mov_b32_e32 v77, v51
	v_mov_b32_e32 v79, v53
	v_mov_b32_e32 v28, v66
	v_mov_b32_e32 v76, v50
	v_mov_b32_e32 v78, v52
	v_mov_b32_e32 v31, v71
	v_mov_b32_e32 v33, v73
	v_mov_b32_e32 v35, v59
	v_mov_b32_e32 v37, v61
	v_mov_b32_e32 v39, v63
	v_mov_b32_e32 v75, v65
	v_mov_b32_e32 v81, v55
	v_mov_b32_e32 v83, v57
	v_mov_b32_e32 v85, v45
	v_mov_b32_e32 v87, v47
	v_mov_b32_e32 v89, v49
	v_mov_b32_e32 v91, v43
	v_permlane32_swap_b32_e32 v68, v26
	v_permlane32_swap_b32_e32 v69, v27
	v_permlane32_swap_b32_e32 v67, v29
	v_permlane32_swap_b32_e32 v51, v77
	v_permlane32_swap_b32_e32 v53, v79
	v_permlane32_swap_b32_e32 v66, v28
	v_mov_b32_e32 v30, v70
	v_mov_b32_e32 v32, v72
	v_mov_b32_e32 v34, v58
	v_mov_b32_e32 v36, v60
	v_mov_b32_e32 v38, v62
	v_mov_b32_e32 v74, v64
	v_permlane32_swap_b32_e32 v50, v76
	v_permlane32_swap_b32_e32 v52, v78
	v_mov_b32_e32 v80, v54
	v_mov_b32_e32 v82, v56
	v_mov_b32_e32 v84, v44
	v_mov_b32_e32 v86, v46
	v_mov_b32_e32 v88, v48
	v_mov_b32_e32 v90, v42
	v_permlane32_swap_b32_e32 v71, v31
	v_permlane32_swap_b32_e32 v73, v33
	v_permlane32_swap_b32_e32 v59, v35
	v_permlane32_swap_b32_e32 v61, v37
	v_permlane32_swap_b32_e32 v63, v39
	v_permlane32_swap_b32_e32 v65, v75
	v_permlane32_swap_b32_e32 v55, v81
	v_permlane32_swap_b32_e32 v57, v83
	v_permlane32_swap_b32_e32 v45, v85
	v_permlane32_swap_b32_e32 v47, v87
	v_permlane32_swap_b32_e32 v49, v89
	v_permlane32_swap_b32_e32 v43, v91
	v_pk_add_f32 v[26:27], v[68:69], v[26:27]
	v_pk_add_f32 v[28:29], v[66:67], v[28:29]
	v_permlane32_swap_b32_e32 v70, v30
	v_permlane32_swap_b32_e32 v72, v32
	s_waitcnt vmcnt(5)
	v_rcp_f32_e32 v2, v2
	v_rcp_f32_e32 v3, v3
	v_rcp_f32_e32 v4, v4
	v_rcp_f32_e32 v5, v5
	s_waitcnt vmcnt(4)
	v_rcp_f32_e32 v6, v6
	v_rcp_f32_e32 v7, v7
	v_rcp_f32_e32 v8, v8
	v_rcp_f32_e32 v9, v9
	s_waitcnt vmcnt(1)
	v_rcp_f32_e32 v18, v18
	v_rcp_f32_e32 v19, v19
	v_rcp_f32_e32 v20, v20
	v_rcp_f32_e32 v21, v21
	s_waitcnt vmcnt(0)
	v_rcp_f32_e32 v22, v22
	v_rcp_f32_e32 v23, v23
	v_rcp_f32_e32 v24, v24
	v_rcp_f32_e32 v25, v25
	v_permlane32_swap_b32_e32 v58, v34
	v_permlane32_swap_b32_e32 v60, v36
	v_permlane32_swap_b32_e32 v62, v38
	v_permlane32_swap_b32_e32 v64, v74
	v_pk_add_f32 v[50:51], v[50:51], v[76:77]
	v_pk_add_f32 v[52:53], v[52:53], v[78:79]
	v_permlane32_swap_b32_e32 v54, v80
	v_permlane32_swap_b32_e32 v56, v82
	v_permlane32_swap_b32_e32 v44, v84
	v_permlane32_swap_b32_e32 v46, v86
	v_permlane32_swap_b32_e32 v48, v88
	v_permlane32_swap_b32_e32 v42, v90
	v_lshl_add_u64 v[0:1], v[40:41], 2, v[106:107]
	v_lshlrev_b32_e32 v40, 16, v10
	v_and_b32_e32 v41, 0xffff0000, v10
	v_lshlrev_b32_e32 v10, 16, v11
	v_and_b32_e32 v11, 0xffff0000, v11
	v_pk_add_f32 v[30:31], v[70:71], v[30:31]
	v_pk_add_f32 v[32:33], v[72:73], v[32:33]
	v_pk_add_f32 v[34:35], v[58:59], v[34:35]
	v_pk_add_f32 v[36:37], v[60:61], v[36:37]
	v_pk_add_f32 v[38:39], v[62:63], v[38:39]
	v_pk_add_f32 v[58:59], v[64:65], v[74:75]
	v_pk_add_f32 v[54:55], v[54:55], v[80:81]
	v_pk_add_f32 v[56:57], v[56:57], v[82:83]
	v_pk_add_f32 v[44:45], v[44:45], v[84:85]
	v_pk_add_f32 v[46:47], v[46:47], v[86:87]
	v_pk_add_f32 v[48:49], v[48:49], v[88:89]
	v_pk_add_f32 v[42:43], v[42:43], v[90:91]
	v_cndmask_b32_e64 v27, v51, v27, s[0:1]
	v_cndmask_b32_e64 v26, v50, v26, s[0:1]
	v_cndmask_b32_e64 v29, v53, v29, s[0:1]
	v_cndmask_b32_e64 v28, v52, v28, s[0:1]
	v_lshlrev_b32_e32 v92, 16, v12
	v_and_b32_e32 v93, 0xffff0000, v12
	v_lshlrev_b32_e32 v12, 16, v13
	v_and_b32_e32 v13, 0xffff0000, v13
	v_lshlrev_b32_e32 v94, 16, v14
	v_and_b32_e32 v95, 0xffff0000, v14
	v_lshlrev_b32_e32 v14, 16, v15
	v_and_b32_e32 v15, 0xffff0000, v15
	v_lshlrev_b32_e32 v96, 16, v16
	v_and_b32_e32 v97, 0xffff0000, v16
	v_lshlrev_b32_e32 v16, 16, v17
	v_and_b32_e32 v17, 0xffff0000, v17
	v_cndmask_b32_e64 v31, v55, v31, s[0:1]
	v_cndmask_b32_e64 v30, v54, v30, s[0:1]
	v_cndmask_b32_e64 v33, v57, v33, s[0:1]
	v_cndmask_b32_e64 v32, v56, v32, s[0:1]
	v_cndmask_b32_e64 v35, v45, v35, s[0:1]
	v_cndmask_b32_e64 v34, v44, v34, s[0:1]
	v_cndmask_b32_e64 v37, v47, v37, s[0:1]
	v_cndmask_b32_e64 v36, v46, v36, s[0:1]
	v_cndmask_b32_e64 v39, v49, v39, s[0:1]
	v_cndmask_b32_e64 v38, v48, v38, s[0:1]
	v_cndmask_b32_e64 v43, v43, v59, s[0:1]
	v_cndmask_b32_e64 v42, v42, v58, s[0:1]
	v_pk_fma_f32 v[2:3], v[2:3], v[40:41], v[26:27]
	v_pk_fma_f32 v[4:5], v[4:5], v[10:11], v[28:29]
	v_pk_fma_f32 v[6:7], v[6:7], v[92:93], v[30:31]
	v_pk_fma_f32 v[8:9], v[8:9], v[12:13], v[32:33]
	v_pk_fma_f32 v[10:11], v[18:19], v[94:95], v[34:35]
	v_pk_fma_f32 v[12:13], v[20:21], v[14:15], v[36:37]
	v_pk_fma_f32 v[14:15], v[22:23], v[96:97], v[38:39]
	v_pk_fma_f32 v[16:17], v[24:25], v[16:17], v[42:43]
	global_store_dwordx4 v[0:1], v[2:5], off
	global_store_dwordx4 v[0:1], v[6:9], off offset:16
	global_store_dwordx4 v[0:1], v[10:13], off offset:32
	global_store_dwordx4 v[0:1], v[14:17], off offset:48
.Lp5_v_next:
	s_or_b64 exec, exec, s[16:17]
	s_add_i32 s85, s85, 1
	s_cmp_eq_u32 s85, 8
	s_cbranch_scc0 .Lp5_v_head
	s_branch .LBB0_1379
